# layer-1 weight transposes moved out of phase 0 into layer 0's in-projection phase tail: done (2 batches of 3 tiles, loads batched) by the 168 workgroups that have 5 instead of 6 in-projection tiles; p
# speedup vs baseline: 1.0023x; 1.0023x over previous
.LBB0_294:
	s_setprio 0
	s_cmp_lg_u32 s50, 0
	s_cbranch_scc1 .Lpi_skip
	s_lshr_b32 s5, s96, 3
	s_cmpk_lt_u32 s5, 43
	s_cbranch_scc1 .Lpi_skip
	s_sub_i32 s5, s5, 43
	s_lshl_b32 s5, s5, 3
	s_and_b32 s0, s96, 7
	s_or_b32 s5, s5, s0
	s_mov_b32 s2, 0
	v_readlane_b32 s24, v207, 18
	v_readlane_b32 s25, v207, 19
	v_readlane_b32 s26, v207, 34
	v_readlane_b32 s27, v207, 35
	s_add_u32 s28, s94, 0xd00000
	s_addc_u32 s29, s95, 0
	s_add_u32 s30, s94, 0x200000
	s_addc_u32 s31, s95, 0
	v_lshrrev_b32_e32 v22, 4, v138
	v_and_b32_e32 v0, 15, v138
	v_lshlrev_b32_e32 v0, 4, v0
	v_and_b32_e32 v2, 3, v138
	v_lshlrev_b32_e32 v24, 4, v2
	v_lshlrev_b32_e32 v2, 5, v2
	v_lshrrev_b32_e32 v23, 2, v138
	v_mul_u32_u24_e32 v24, 0x41, v24
	v_and_b32_e32 v25, -4, v138
	v_lshl_add_u32 v24, v24, 2, v25
	v_mul_u32_u24_e32 v25, 0x104, v22
	v_add_u32_e32 v25, v25, v0
	v_add_u32_e32 v26, 0x1040, v25
	v_add_u32_e32 v27, 0x1048, v25
	v_add_u32_e32 v28, 0x2080, v25
	v_add_u32_e32 v29, 0x2088, v25
	v_add_u32_e32 v30, 0x30c0, v25
	v_add_u32_e32 v31, 0x30c8, v25
	v_add_u32_e32 v83, 0x400, v24
	v_add_u32_e32 v84, 0x800, v24
	v_add_u32_e32 v85, 0xc00, v24
.Lpi_again:
	v_lshl_add_u32 v82, v23, 11, v2
	s_mov_b32 s1, s5
	s_movk_i32 s86, 0x3c0
	s_cmpk_lt_u32 s1, 0x2c0
	s_cselect_b32 s86, 0x2c0, s86
	s_add_i32 s1, s1, s86
	s_cmpk_gt_i32 s1, 0x57f
	s_cbranch_scc1 .Lpi_out0
	s_mul_hi_i32 s86, s1, 0x2e8ba2e9
	s_ashr_i32 s86, s86, 7
	s_mul_i32 s87, s86, 0x2c0
	s_sub_i32 s87, s1, s87
	s_mul_i32 s88, s87, 0xba3
	s_lshr_b32 s88, s88, 17
	s_mul_i32 s89, s88, 44
	s_sub_i32 s87, s87, s89
	s_mul_i32 s89, s86, 0xb00000
	s_mul_i32 s90, s88, 0xb0000
	s_add_u32 s89, s89, s90
	s_lshl_b32 s90, s87, 8
	s_add_u32 s89, s89, s90
	s_add_u32 s76, s24, s89
	s_addc_u32 s77, s25, 0
	s_sub_i32 s90, s87, 20
	s_cmp_gt_u32 s90, 15
	s_cbranch_scc1 .Lpi_nr0
	s_and_b32 s91, s87, 3
	s_lshr_b32 s90, s90, 2
	s_lshl_b32 s90, s90, 3
	s_lshr_b32 s90, 0x1d15141c, s90
	s_and_b32 s90, s90, 0xff
	s_lshl_b32 s91, s91, 1
	s_add_i32 s87, s90, s91

.Lpi_dec0:
	v_mad_u32_u24 v72, v22, s80, v0
	s_lshl_b32 s0, s80, 4
	global_load_dwordx4 v[4:7], v72, s[76:77] nt
	s_add_u32 s76, s76, s0
	s_addc_u32 s77, s77, 0
	global_load_dwordx4 v[8:11], v72, s[76:77] nt
	s_add_u32 s76, s76, s0
	s_addc_u32 s77, s77, 0
	global_load_dwordx4 v[12:15], v72, s[76:77] nt
	s_add_u32 s76, s76, s0
	s_addc_u32 s77, s77, 0
	global_load_dwordx4 v[16:19], v72, s[76:77] nt
	s_add_i32 s1, s5, 0xa8
	s_movk_i32 s86, 0x3c0
	s_cmpk_lt_u32 s1, 0x2c0
	s_cselect_b32 s86, 0x2c0, s86
	s_add_i32 s1, s1, s86
	s_cmpk_gt_i32 s1, 0x57f
	s_cbranch_scc1 .Lpi_out1
	s_mul_hi_i32 s86, s1, 0x2e8ba2e9
	s_ashr_i32 s86, s86, 7
	s_mul_i32 s87, s86, 0x2c0
	s_sub_i32 s87, s1, s87
	s_mul_i32 s88, s87, 0xba3
	s_lshr_b32 s88, s88, 17
	s_mul_i32 s89, s88, 44
	s_sub_i32 s87, s87, s89
	s_mul_i32 s89, s86, 0xb00000
	s_mul_i32 s90, s88, 0xb0000
	s_add_u32 s89, s89, s90
	s_lshl_b32 s90, s87, 8
	s_add_u32 s89, s89, s90
	s_add_u32 s82, s24, s89
	s_addc_u32 s83, s25, 0
	s_sub_i32 s90, s87, 20
	s_cmp_gt_u32 s90, 15
	s_cbranch_scc1 .Lpi_nr1
	s_and_b32 s91, s87, 3
	s_lshr_b32 s90, s90, 2
	s_lshl_b32 s90, s90, 3
	s_lshr_b32 s90, 0x1d15141c, s90
	s_and_b32 s90, s90, 0xff
	s_lshl_b32 s91, s91, 1
	s_add_i32 s87, s90, s91

.Lpi_dec1:
	v_mad_u32_u24 v73, v22, s81, v0
	s_lshl_b32 s0, s81, 4
	global_load_dwordx4 v[208:211], v73, s[82:83] nt
	s_add_u32 s82, s82, s0
	s_addc_u32 s83, s83, 0
	global_load_dwordx4 v[212:215], v73, s[82:83] nt
	s_add_u32 s82, s82, s0
	s_addc_u32 s83, s83, 0
	global_load_dwordx4 v[216:219], v73, s[82:83] nt
	s_add_u32 s82, s82, s0
	s_addc_u32 s83, s83, 0
	global_load_dwordx4 v[220:223], v73, s[82:83] nt
	s_add_i32 s1, s5, 0x150
	s_cmpk_gt_u32 s1, 0x3bf
	s_cbranch_scc1 .Lpi_dummy
	s_movk_i32 s86, 0x3c0
	s_cmpk_lt_u32 s1, 0x2c0
	s_cselect_b32 s86, 0x2c0, s86
	s_add_i32 s1, s1, s86
	s_cmpk_gt_i32 s1, 0x57f
	s_cbranch_scc1 .Lpi_out2
	s_mul_hi_i32 s86, s1, 0x2e8ba2e9
	s_ashr_i32 s86, s86, 7
	s_mul_i32 s87, s86, 0x2c0
	s_sub_i32 s87, s1, s87
	s_mul_i32 s88, s87, 0xba3
	s_lshr_b32 s88, s88, 17
	s_mul_i32 s89, s88, 44
	s_sub_i32 s87, s87, s89
	s_mul_i32 s89, s86, 0xb00000
	s_mul_i32 s90, s88, 0xb0000
	s_add_u32 s89, s89, s90
	s_lshl_b32 s90, s87, 8
	s_add_u32 s89, s89, s90
	s_add_u32 s20, s24, s89
	s_addc_u32 s21, s25, 0
	s_sub_i32 s90, s87, 20
	s_cmp_gt_u32 s90, 15
	s_cbranch_scc1 .Lpi_nr2
	s_and_b32 s91, s87, 3
	s_lshr_b32 s90, s90, 2
	s_lshl_b32 s90, s90, 3
	s_lshr_b32 s90, 0x1d15141c, s90
	s_and_b32 s90, s90, 0xff
	s_lshl_b32 s91, s91, 1
	s_add_i32 s87, s90, s91

.Lpi_done:
	s_add_i32 s5, s5, 0x1f8
	s_add_i32 s2, s2, 1
	s_cmp_lt_u32 s2, 2
	s_cbranch_scc1 .Lpi_again
